# v047 + final-phase GEMM epilogue: U loads prefetched 4 row-groups ahead, unpack+acc first, then stores/LDS atomics
# baseline (speedup 1.0000x reference)
; #define G_STAGE(bufoff, gbase, voff) do { _Pragma("unroll") for (int _i = 0; _i < 2; ++_i) \
;         __builtin_amdgcn_global_load_lds((const unsigned*)((const char*)(gbase) + (voff)[_i]), (LAS unsigned*)(lds + (bufoff) + ldsw + _i * 8192), 16, 0, 0); } while (0)
; #define G_LDA(dst, b, h) do { _Pragma("unroll") for (int m = 0; m < 4; ++m) _Pragma("unroll") for (int k = 0; k < 2; ++k) dst[m][k] = *(const LAS bf16x8*)(lds + G_SA(b, h) + aoff + m * 2048 + k * 1024); } while (0)
; #define G_LDB(dst, b, h) do { _Pragma("unroll") for (int n = 0; n < 2; ++n) _Pragma("unroll") for (int k = 0; k < 2; ++k) dst[n][k] = *(const LAS bf16x8*)(lds + G_SB(b, h) + boff + n * 2048 + k * 1024); } while (0)
; #define G_WAIT_V(n) asm volatile("s_waitcnt vmcnt(" #n ")" ::: "memory")
; #define G_WAIT_L(n) asm volatile("s_waitcnt lgkmcnt(" #n ")" ::: "memory")
; #define G_BAR __builtin_amdgcn_s_barrier()
; #define G_SCHED __builtin_amdgcn_sched_barrier(0)
; template <bool PERM, class Dec, class Epi>
; DI void gemm_phase(LAS unsigned char* lds, const int nM, const int nN, const int K, const int lda, const int ldb, const Dec& dec, const Epi& epi, const int vb, const int panel = -1) {
;     ...
;             G_LDB(B0, 0, 0); G_SCHED; G_LDA(At, 0, 0); G_STAGE(G_SA(1, 1), a1 + hstepA, voffA);
;             G_WAIT_L(8); G_BAR; G_WAIT_L(0); G_MMA(0, 0, At, B0); G_BAR; G_SCHED;
;             G_LDB(B1, 0, 1); G_STAGE(G_SB(0, 0), b2, voffB);
;             G_BAR; G_WAIT_L(0); G_MMA(0, 1, At, B1); G_BAR;
;             G_LDA(At, 0, 1); G_STAGE(G_SA(0, 0), a2, voffA);
;             G_BAR; G_WAIT_L(0); G_MMA(1, 0, At, B0); G_BAR; G_SCHED;
;             G_STAGE(G_SB(0, 1), b2 + hstepB, voffB);
;             G_WAIT_V(6); G_BAR; G_MMA(1, 1, At, B1); G_BAR;
;             G_LDB(B0, 1, 0); G_SCHED; G_LDA(At, 1, 0); G_STAGE(G_SA(0, 1), a2 + hstepA, voffA);
;             G_WAIT_L(8); G_BAR; G_WAIT_L(0); G_MMA(0, 0, At, B0); G_BAR; G_SCHED;
;             G_LDB(B1, 1, 1); G_STAGE(G_SB(1, 0), b3, voffB);
;             G_BAR; G_WAIT_L(0); G_MMA(0, 1, At, B1); G_BAR;
;             G_LDA(At, 1, 1); G_STAGE(G_SA(1, 0), a3, voffA);
;             G_BAR; G_WAIT_L(0); G_MMA(1, 0, At, B0); G_BAR; G_SCHED;
;             G_STAGE(G_SB(1, 1), b3 + hstepB, voffB);
;             G_WAIT_V(6); G_BAR; G_MMA(1, 1, At, B1); G_BAR;
.LBB0_924:
	s_add_u32 s22, s18, 0x100
	s_addc_u32 s23, s19, 0
	s_add_i32 s53, 0, 0x10000
	v_add_u32_e32 v140, s53, v144
	ds_read_b128 v[162:165], v140
	ds_read_b128 v[166:169], v140 offset:1024
	ds_read_b128 v[170:173], v140 offset:2048
	ds_read_b128 v[176:179], v140 offset:3072
	s_cmp_eq_u32 s52, 20
	s_cselect_b32 s29, s13, s23
	s_cselect_b32 s28, s12, s22
	s_cselect_b32 s25, s17, s51
	s_cselect_b32 s24, s16, s50
	v_lshl_add_u64 v[140:141], s[18:19], 0, v[136:137]
	s_add_i32 m0, s39, 0xc000
	ds_read_b128 v[180:183], v160
	ds_read_b128 v[184:187], v160 offset:1024
	ds_read_b128 v[188:191], v160 offset:2048
	ds_read_b128 v[194:197], v160 offset:3072
	ds_read_b128 v[198:201], v160 offset:4096
	ds_read_b128 v[202:205], v160 offset:5120
	ds_read_b128 v[206:209], v160 offset:6144
	ds_read_b128 v[210:213], v160 offset:7168
	global_load_lds_dwordx4 v[140:141], off
	v_lshl_add_u64 v[140:141], s[18:19], 0, v[138:139]
	s_add_i32 m0, s39, 0xe000
	s_nop 0
	global_load_lds_dwordx4 v[140:141], off
	s_waitcnt lgkmcnt(8)
	s_barrier
	s_waitcnt lgkmcnt(0)
	s_setprio 1
	s_waitcnt lgkmcnt(0)
	v_mfma_f32_16x16x32_bf16 v[124:127], v[162:165], v[180:183], v[124:127]
	v_mfma_f32_16x16x32_bf16 v[120:123], v[170:173], v[180:183], v[120:123]
	v_mfma_f32_16x16x32_bf16 v[108:111], v[162:165], v[188:191], v[108:111]
	v_mfma_f32_16x16x32_bf16 v[104:107], v[170:173], v[188:191], v[104:107]
	v_mfma_f32_16x16x32_bf16 v[92:95], v[162:165], v[198:201], v[92:95]
	v_mfma_f32_16x16x32_bf16 v[88:91], v[170:173], v[198:201], v[88:91]
	v_mfma_f32_16x16x32_bf16 v[76:79], v[162:165], v[206:209], v[76:79]
	v_mfma_f32_16x16x32_bf16 v[72:75], v[170:173], v[206:209], v[72:75]
	v_mfma_f32_16x16x32_bf16 v[124:127], v[166:169], v[184:187], v[124:127]
	v_mfma_f32_16x16x32_bf16 v[120:123], v[176:179], v[184:187], v[120:123]
	v_mfma_f32_16x16x32_bf16 v[108:111], v[166:169], v[194:197], v[108:111]
	v_mfma_f32_16x16x32_bf16 v[104:107], v[176:179], v[194:197], v[104:107]
	v_mfma_f32_16x16x32_bf16 v[92:95], v[166:169], v[202:205], v[92:95]
	v_mfma_f32_16x16x32_bf16 v[88:91], v[176:179], v[202:205], v[88:91]
	v_mfma_f32_16x16x32_bf16 v[76:79], v[166:169], v[210:213], v[76:79]
	v_mfma_f32_16x16x32_bf16 v[72:75], v[176:179], v[210:213], v[72:75]
	s_setprio 0
	s_barrier
	s_add_i32 s54, 0, 0x14000
	v_add_u32_e32 v140, s54, v144
	s_add_i32 s18, s53, s38
	ds_read_b128 v[214:217], v140
	ds_read_b128 v[218:221], v140 offset:1024
	ds_read_b128 v[222:225], v140 offset:2048
	ds_read_b128 v[226:229], v140 offset:3072
	v_lshl_add_u64 v[140:141], s[24:25], 0, v[128:129]
	s_mov_b32 m0, s18
	v_lshl_add_u64 v[230:231], s[24:25], 0, v[132:133]
	global_load_lds_dwordx4 v[140:141], off
	s_add_i32 m0, s18, 0x2000
	s_nop 0
	global_load_lds_dwordx4 v[230:231], off
	s_barrier
	s_waitcnt lgkmcnt(0)
	s_setprio 1
	s_waitcnt lgkmcnt(0)
	v_mfma_f32_16x16x32_bf16 v[116:119], v[214:217], v[180:183], v[116:119]
	v_mfma_f32_16x16x32_bf16 v[112:115], v[222:225], v[180:183], v[112:115]
	v_mfma_f32_16x16x32_bf16 v[100:103], v[214:217], v[188:191], v[100:103]
	v_mfma_f32_16x16x32_bf16 v[96:99], v[222:225], v[188:191], v[96:99]
	v_mfma_f32_16x16x32_bf16 v[84:87], v[214:217], v[198:201], v[84:87]
	v_mfma_f32_16x16x32_bf16 v[80:83], v[222:225], v[198:201], v[80:83]
	v_mfma_f32_16x16x32_bf16 v[68:71], v[214:217], v[206:209], v[68:71]
	v_mfma_f32_16x16x32_bf16 v[64:67], v[222:225], v[206:209], v[64:67]
	v_mfma_f32_16x16x32_bf16 v[116:119], v[218:221], v[184:187], v[116:119]
	v_mfma_f32_16x16x32_bf16 v[112:115], v[226:229], v[184:187], v[112:115]
	v_mfma_f32_16x16x32_bf16 v[100:103], v[218:221], v[194:197], v[100:103]
	v_mfma_f32_16x16x32_bf16 v[96:99], v[226:229], v[194:197], v[96:99]
	v_mfma_f32_16x16x32_bf16 v[84:87], v[218:221], v[202:205], v[84:87]
	v_mfma_f32_16x16x32_bf16 v[80:83], v[226:229], v[202:205], v[80:83]
	v_mfma_f32_16x16x32_bf16 v[68:71], v[218:221], v[210:213], v[68:71]
	v_mfma_f32_16x16x32_bf16 v[64:67], v[226:229], v[210:213], v[64:67]
	s_setprio 0
	s_mov_b32 m0, s39
	v_lshl_add_u64 v[232:233], s[28:29], 0, v[128:129]
	s_barrier
	ds_read_b128 v[180:183], v160 offset:16384
	ds_read_b128 v[184:187], v160 offset:17408
	ds_read_b128 v[188:191], v160 offset:18432
	ds_read_b128 v[194:197], v160 offset:19456
	ds_read_b128 v[198:201], v160 offset:20480
	ds_read_b128 v[202:205], v160 offset:21504
	ds_read_b128 v[206:209], v160 offset:22528
	ds_read_b128 v[210:213], v160 offset:23552
	global_load_lds_dwordx4 v[232:233], off
	v_lshl_add_u64 v[234:235], s[28:29], 0, v[132:133]
	s_mov_b32 m0, s40
	s_nop 0
	global_load_lds_dwordx4 v[234:235], off
	s_barrier
	s_waitcnt lgkmcnt(0)
	s_setprio 1
	s_waitcnt lgkmcnt(0)
	v_mfma_f32_16x16x32_bf16 v[60:63], v[162:165], v[180:183], v[60:63]
	v_mfma_f32_16x16x32_bf16 v[56:59], v[170:173], v[180:183], v[56:59]
	v_mfma_f32_16x16x32_bf16 v[44:47], v[162:165], v[188:191], v[44:47]
	v_mfma_f32_16x16x32_bf16 v[40:43], v[170:173], v[188:191], v[40:43]
	v_mfma_f32_16x16x32_bf16 v[28:31], v[162:165], v[198:201], v[28:31]
	v_mfma_f32_16x16x32_bf16 v[24:27], v[170:173], v[198:201], v[24:27]
	v_mfma_f32_16x16x32_bf16 v[12:15], v[162:165], v[206:209], v[12:15]
	v_mfma_f32_16x16x32_bf16 v[8:11], v[170:173], v[206:209], v[8:11]
	v_mfma_f32_16x16x32_bf16 v[60:63], v[166:169], v[184:187], v[60:63]
	v_mfma_f32_16x16x32_bf16 v[56:59], v[176:179], v[184:187], v[56:59]
	v_mfma_f32_16x16x32_bf16 v[44:47], v[166:169], v[194:197], v[44:47]
	v_mfma_f32_16x16x32_bf16 v[40:43], v[176:179], v[194:197], v[40:43]
	v_mfma_f32_16x16x32_bf16 v[28:31], v[166:169], v[202:205], v[28:31]
	v_mfma_f32_16x16x32_bf16 v[24:27], v[176:179], v[202:205], v[24:27]
	v_mfma_f32_16x16x32_bf16 v[12:15], v[166:169], v[210:213], v[12:15]
	v_mfma_f32_16x16x32_bf16 v[8:11], v[176:179], v[210:213], v[8:11]
	s_setprio 0
	s_barrier
; #define G_STAGE(bufoff, gbase, voff) do { _Pragma("unroll") for (int _i = 0; _i < 2; ++_i) \
;         __builtin_amdgcn_global_load_lds((const unsigned*)((const char*)(gbase) + (voff)[_i]), (LAS unsigned*)(lds + (bufoff) + ldsw + _i * 8192), 16, 0, 0); } while (0)
; #define G_LDA(dst, b, h) do { _Pragma("unroll") for (int m = 0; m < 4; ++m) _Pragma("unroll") for (int k = 0; k < 2; ++k) dst[m][k] = *(const LAS bf16x8*)(lds + G_SA(b, h) + aoff + m * 2048 + k * 1024); } while (0)
; #define G_LDB(dst, b, h) do { _Pragma("unroll") for (int n = 0; n < 2; ++n) _Pragma("unroll") for (int k = 0; k < 2; ++k) dst[n][k] = *(const LAS bf16x8*)(lds + G_SB(b, h) + boff + n * 2048 + k * 1024); } while (0)
; #define G_MMA(ai, bj, At, Bt) do { __builtin_amdgcn_s_setprio(1); _Pragma("unroll") for (int m = 0; m < 4; ++m) _Pragma("unroll") for (int n = 0; n < 2; ++n) _Pragma("unroll") for (int k = 0; k < 2; ++k) \
;         acc[ai][bj][m][n] = __builtin_amdgcn_mfma_f32_16x16x32_bf16(Bt[n][k], At[m][k], acc[ai][bj][m][n], 0, 0, 0); __builtin_amdgcn_s_setprio(0); } while (0)
; #define G_WAIT_V(n) asm volatile("s_waitcnt vmcnt(" #n ")" ::: "memory")
; #define G_WAIT_L(n) asm volatile("s_waitcnt lgkmcnt(" #n ")" ::: "memory")
; #define G_BAR __builtin_amdgcn_s_barrier()
; #define G_SCHED __builtin_amdgcn_sched_barrier(0)
; template <bool PERM, class Dec, class Epi>
; DI void gemm_phase(LAS unsigned char* lds, const int nM, const int nN, const int K, const int lda, const int ldb, const Dec& dec, const Epi& epi, const int vb, const int panel = -1) {
;     ...
;             G_LDB(B0, 1, 0); G_SCHED; G_LDA(At, 1, 0); G_STAGE(G_SA(0, 1), a2 + hstepA, voffA);
;             G_WAIT_L(8); G_BAR; G_WAIT_L(0); G_MMA(0, 0, At, B0); G_BAR; G_SCHED;
;             G_LDB(B1, 1, 1); G_STAGE(G_SB(1, 0), b3, voffB);
;             G_BAR; G_WAIT_L(0); G_MMA(0, 1, At, B1); G_BAR;
;             G_LDA(At, 1, 1); G_STAGE(G_SA(1, 0), a3, voffA);
;             G_BAR; G_WAIT_L(0); G_MMA(1, 0, At, B0); G_BAR; G_SCHED;
;             G_STAGE(G_SB(1, 1), b3 + hstepB, voffB);
;             G_WAIT_V(6); G_BAR; G_MMA(1, 1, At, B1); G_BAR;
	s_add_u32 s18, s24, 0x60000
	s_addc_u32 s19, s25, 0
	s_add_i32 s53, s54, s38
	v_lshl_add_u64 v[162:163], s[18:19], 0, v[128:129]
	s_mov_b32 m0, s53
	s_nop 0
	global_load_lds_dwordx4 v[162:163], off
	v_lshl_add_u64 v[162:163], s[18:19], 0, v[132:133]
	s_add_i32 m0, s53, 0x2000
	s_nop 0
	global_load_lds_dwordx4 v[162:163], off
	s_waitcnt vmcnt(6)
	s_barrier
	s_setprio 1
	v_mfma_f32_16x16x32_bf16 v[52:55], v[214:217], v[180:183], v[52:55]
	v_mfma_f32_16x16x32_bf16 v[48:51], v[222:225], v[180:183], v[48:51]
	v_mfma_f32_16x16x32_bf16 v[36:39], v[214:217], v[188:191], v[36:39]
	v_mfma_f32_16x16x32_bf16 v[32:35], v[222:225], v[188:191], v[32:35]
	v_mfma_f32_16x16x32_bf16 v[20:23], v[214:217], v[198:201], v[20:23]
	v_mfma_f32_16x16x32_bf16 v[16:19], v[222:225], v[198:201], v[16:19]
	v_mfma_f32_16x16x32_bf16 v[4:7], v[214:217], v[206:209], v[4:7]
	v_mfma_f32_16x16x32_bf16 v[0:3], v[222:225], v[206:209], v[0:3]
	v_mfma_f32_16x16x32_bf16 v[52:55], v[218:221], v[184:187], v[52:55]
	v_mfma_f32_16x16x32_bf16 v[48:51], v[226:229], v[184:187], v[48:51]
	v_mfma_f32_16x16x32_bf16 v[36:39], v[218:221], v[194:197], v[36:39]
	v_mfma_f32_16x16x32_bf16 v[32:35], v[226:229], v[194:197], v[32:35]
	v_mfma_f32_16x16x32_bf16 v[20:23], v[218:221], v[202:205], v[20:23]
	v_mfma_f32_16x16x32_bf16 v[16:19], v[226:229], v[202:205], v[16:19]
	v_mfma_f32_16x16x32_bf16 v[4:7], v[218:221], v[210:213], v[4:7]
	v_mfma_f32_16x16x32_bf16 v[0:3], v[226:229], v[210:213], v[0:3]
	s_setprio 0
	s_add_i32 s53, 0, 0x18000
	v_add_u32_e32 v161, s53, v144
	s_barrier
	ds_read_b128 v[162:165], v161
	ds_read_b128 v[166:169], v161 offset:1024
	ds_read_b128 v[170:173], v161 offset:2048
	ds_read_b128 v[176:179], v161 offset:3072
	s_add_u32 s18, s28, 0x60000
	s_addc_u32 s19, s29, 0
	s_mov_b32 m0, s41
	v_lshl_add_u64 v[214:215], s[18:19], 0, v[128:129]
	ds_read_b128 v[180:183], v160 offset:32768
	ds_read_b128 v[184:187], v160 offset:33792
	ds_read_b128 v[188:191], v160 offset:34816
	ds_read_b128 v[194:197], v160 offset:35840
	ds_read_b128 v[198:201], v160 offset:36864
	ds_read_b128 v[202:205], v160 offset:37888
	ds_read_b128 v[206:209], v160 offset:38912
	ds_read_b128 v[210:213], v160 offset:39936
	global_load_lds_dwordx4 v[214:215], off
	v_lshl_add_u64 v[214:215], s[18:19], 0, v[132:133]
	s_mov_b32 m0, s42
	s_nop 0
	global_load_lds_dwordx4 v[214:215], off
	s_waitcnt lgkmcnt(8)
	s_barrier
	s_waitcnt lgkmcnt(0)
	s_setprio 1
	s_waitcnt lgkmcnt(0)
	v_mfma_f32_16x16x32_bf16 v[124:127], v[162:165], v[180:183], v[124:127]
	v_mfma_f32_16x16x32_bf16 v[120:123], v[170:173], v[180:183], v[120:123]
	v_mfma_f32_16x16x32_bf16 v[108:111], v[162:165], v[188:191], v[108:111]
	v_mfma_f32_16x16x32_bf16 v[104:107], v[170:173], v[188:191], v[104:107]
	v_mfma_f32_16x16x32_bf16 v[92:95], v[162:165], v[198:201], v[92:95]
	v_mfma_f32_16x16x32_bf16 v[88:91], v[170:173], v[198:201], v[88:91]
	v_mfma_f32_16x16x32_bf16 v[76:79], v[162:165], v[206:209], v[76:79]
	v_mfma_f32_16x16x32_bf16 v[72:75], v[170:173], v[206:209], v[72:75]
	v_mfma_f32_16x16x32_bf16 v[124:127], v[166:169], v[184:187], v[124:127]
	v_mfma_f32_16x16x32_bf16 v[120:123], v[176:179], v[184:187], v[120:123]
	v_mfma_f32_16x16x32_bf16 v[108:111], v[166:169], v[194:197], v[108:111]
	v_mfma_f32_16x16x32_bf16 v[104:107], v[176:179], v[194:197], v[104:107]
	v_mfma_f32_16x16x32_bf16 v[92:95], v[166:169], v[202:205], v[92:95]
	v_mfma_f32_16x16x32_bf16 v[88:91], v[176:179], v[202:205], v[88:91]
	v_mfma_f32_16x16x32_bf16 v[76:79], v[166:169], v[210:213], v[76:79]
	v_mfma_f32_16x16x32_bf16 v[72:75], v[176:179], v[210:213], v[72:75]
	s_setprio 0
	s_barrier
	s_add_i32 s28, 0, 0x1c000
	s_add_i32 s18, s53, s38
	v_add_u32_e32 v161, s28, v144
	v_lshl_add_u64 v[140:141], v[140:141], 0, s[2:3]
	s_mov_b32 m0, s18
	ds_read_b128 v[214:217], v161
	ds_read_b128 v[218:221], v161 offset:1024
	ds_read_b128 v[222:225], v161 offset:2048
	ds_read_b128 v[226:229], v161 offset:3072
	global_load_lds_dwordx4 v[140:141], off
	v_lshl_add_u64 v[140:141], v[230:231], 0, s[2:3]
	s_add_i32 m0, s18, 0x2000
	s_nop 0
	global_load_lds_dwordx4 v[140:141], off
	s_barrier
	s_waitcnt lgkmcnt(0)
	s_setprio 1
	s_waitcnt lgkmcnt(0)
	v_mfma_f32_16x16x32_bf16 v[116:119], v[214:217], v[180:183], v[116:119]
	v_mfma_f32_16x16x32_bf16 v[112:115], v[222:225], v[180:183], v[112:115]
	v_mfma_f32_16x16x32_bf16 v[100:103], v[214:217], v[188:191], v[100:103]
	v_mfma_f32_16x16x32_bf16 v[96:99], v[222:225], v[188:191], v[96:99]
	v_mfma_f32_16x16x32_bf16 v[84:87], v[214:217], v[198:201], v[84:87]
	v_mfma_f32_16x16x32_bf16 v[80:83], v[222:225], v[198:201], v[80:83]
	v_mfma_f32_16x16x32_bf16 v[68:71], v[214:217], v[206:209], v[68:71]
	v_mfma_f32_16x16x32_bf16 v[64:67], v[222:225], v[206:209], v[64:67]
	v_mfma_f32_16x16x32_bf16 v[116:119], v[218:221], v[184:187], v[116:119]
	v_mfma_f32_16x16x32_bf16 v[112:115], v[226:229], v[184:187], v[112:115]
	v_mfma_f32_16x16x32_bf16 v[100:103], v[218:221], v[194:197], v[100:103]
	v_mfma_f32_16x16x32_bf16 v[96:99], v[226:229], v[194:197], v[96:99]
	v_mfma_f32_16x16x32_bf16 v[84:87], v[218:221], v[202:205], v[84:87]
	v_mfma_f32_16x16x32_bf16 v[80:83], v[226:229], v[202:205], v[80:83]
	v_mfma_f32_16x16x32_bf16 v[68:71], v[218:221], v[210:213], v[68:71]
	v_mfma_f32_16x16x32_bf16 v[64:67], v[226:229], v[210:213], v[64:67]
	s_setprio 0
	s_mov_b32 m0, s43
	v_lshl_add_u64 v[140:141], v[232:233], 0, s[2:3]
	s_barrier
	ds_read_b128 v[180:183], v160 offset:49152
	ds_read_b128 v[184:187], v160 offset:50176
	ds_read_b128 v[188:191], v160 offset:51200
	ds_read_b128 v[194:197], v160 offset:52224
	ds_read_b128 v[198:201], v160 offset:53248
	ds_read_b128 v[202:205], v160 offset:54272
	ds_read_b128 v[206:209], v160 offset:55296
	ds_read_b128 v[210:213], v160 offset:56320
	global_load_lds_dwordx4 v[140:141], off
	v_lshl_add_u64 v[140:141], v[234:235], 0, s[2:3]
	s_mov_b32 m0, s44
	s_nop 0
	global_load_lds_dwordx4 v[140:141], off
	s_barrier
; DI float bflo(unsigned u) { return __uint_as_float(u << 16); }
; DI float bfhi(unsigned u) { return __uint_as_float(u & 0xffff0000u); }
; #define G_STAGE(bufoff, gbase, voff) do { _Pragma("unroll") for (int _i = 0; _i < 2; ++_i) \
;         __builtin_amdgcn_global_load_lds((const unsigned*)((const char*)(gbase) + (voff)[_i]), (LAS unsigned*)(lds + (bufoff) + ldsw + _i * 8192), 16, 0, 0); } while (0)
; #define G_LDA(dst, b, h) do { _Pragma("unroll") for (int m = 0; m < 4; ++m) _Pragma("unroll") for (int k = 0; k < 2; ++k) dst[m][k] = *(const LAS bf16x8*)(lds + G_SA(b, h) + aoff + m * 2048 + k * 1024); } while (0)
; #define G_MMA(ai, bj, At, Bt) do { __builtin_amdgcn_s_setprio(1); _Pragma("unroll") for (int m = 0; m < 4; ++m) _Pragma("unroll") for (int n = 0; n < 2; ++n) _Pragma("unroll") for (int k = 0; k < 2; ++k) \
;         acc[ai][bj][m][n] = __builtin_amdgcn_mfma_f32_16x16x32_bf16(Bt[n][k], At[m][k], acc[ai][bj][m][n], 0, 0, 0); __builtin_amdgcn_s_setprio(0); } while (0)
; template <bool PERM, class Dec, class Epi>
; DI void gemm_phase(LAS unsigned char* lds, const int nM, const int nN, const int K, const int lda, const int ldb, const Dec& dec, const Epi& epi, const int vb, const int panel = -1) {
;     ...
;             G_BAR; G_WAIT_L(0); G_MMA(0, 1, At, B1); G_BAR;
;             G_LDA(At, 1, 1); G_STAGE(G_SA(1, 0), a3, voffA);
;             G_BAR; G_WAIT_L(0); G_MMA(1, 0, At, B0); G_BAR; G_SCHED;
;             G_STAGE(G_SB(1, 1), b3 + hstepB, voffB);
;             G_WAIT_V(6); G_BAR; G_MMA(1, 1, At, B1); G_BAR;
; __global__ void __launch_bounds__(512) hybrid_fwd(Params p) {
;     ...
;               [=](const f32x4 (&acc)[2][2][4][2], int pm, int pn, int wr, int wc, int fr, int fq) {
; #pragma unroll
;                   for (int ai = 0; ai < 2; ++ai)
; #pragma unroll
;                       for (int m = 0; m < 4; ++m) { const int rl = ai * 128 + wr * 64 + m * 16 + fr; const size_t ro = (size_t)(pm * 256 + rl) * 1024 + pn * 256 + wc * 32 + 4 * fq;
;                           float ssq = 0.f;
; #pragma unroll
;                           for (int bj = 0; bj < 2; ++bj)
; #pragma unroll
;                               for (int n = 0; n < 2; ++n) { const size_t o = ro + bj * 128 + n * 16; const u32x2 xb = *(const u32x2*)(U + o);
;                                   const f32x4 v = (f32x4){bflo(xb[0]), bfhi(xb[0]), bflo(xb[1]), bfhi(xb[1])} + acc[ai][bj][m][n];
	s_waitcnt lgkmcnt(0)
	s_setprio 1
	s_waitcnt lgkmcnt(0)
	v_mfma_f32_16x16x32_bf16 v[60:63], v[162:165], v[180:183], v[60:63]
	v_mfma_f32_16x16x32_bf16 v[56:59], v[170:173], v[180:183], v[56:59]
	v_mfma_f32_16x16x32_bf16 v[44:47], v[162:165], v[188:191], v[44:47]
	v_mfma_f32_16x16x32_bf16 v[40:43], v[170:173], v[188:191], v[40:43]
	v_mfma_f32_16x16x32_bf16 v[28:31], v[162:165], v[198:201], v[28:31]
	v_mfma_f32_16x16x32_bf16 v[24:27], v[170:173], v[198:201], v[24:27]
	v_mfma_f32_16x16x32_bf16 v[12:15], v[162:165], v[206:209], v[12:15]
	v_mfma_f32_16x16x32_bf16 v[8:11], v[170:173], v[206:209], v[8:11]
	v_mfma_f32_16x16x32_bf16 v[60:63], v[166:169], v[184:187], v[60:63]
	v_mfma_f32_16x16x32_bf16 v[56:59], v[176:179], v[184:187], v[56:59]
	v_mfma_f32_16x16x32_bf16 v[44:47], v[166:169], v[194:197], v[44:47]
	v_mfma_f32_16x16x32_bf16 v[40:43], v[176:179], v[194:197], v[40:43]
	v_mfma_f32_16x16x32_bf16 v[28:31], v[166:169], v[202:205], v[28:31]
	v_mfma_f32_16x16x32_bf16 v[24:27], v[176:179], v[202:205], v[24:27]
	v_mfma_f32_16x16x32_bf16 v[12:15], v[166:169], v[210:213], v[12:15]
	v_mfma_f32_16x16x32_bf16 v[8:11], v[176:179], v[210:213], v[8:11]
	s_setprio 0
	s_barrier
	s_add_u32 s18, s24, 0x60080
	s_addc_u32 s19, s25, 0
	s_add_i32 s24, s28, s38
	v_lshl_add_u64 v[140:141], s[18:19], 0, v[128:129]
	s_mov_b32 m0, s24
	s_nop 0
	global_load_lds_dwordx4 v[140:141], off
	v_lshl_add_u64 v[140:141], s[18:19], 0, v[132:133]
	s_add_i32 m0, s24, 0x2000
	s_nop 0
	global_load_lds_dwordx4 v[140:141], off
	s_waitcnt vmcnt(6)
	s_barrier
	s_setprio 1
	v_mfma_f32_16x16x32_bf16 v[52:55], v[214:217], v[180:183], v[52:55]
	v_mfma_f32_16x16x32_bf16 v[48:51], v[222:225], v[180:183], v[48:51]
	v_mfma_f32_16x16x32_bf16 v[36:39], v[214:217], v[188:191], v[36:39]
	v_mfma_f32_16x16x32_bf16 v[32:35], v[222:225], v[188:191], v[32:35]
	v_mfma_f32_16x16x32_bf16 v[20:23], v[214:217], v[198:201], v[20:23]
	v_mfma_f32_16x16x32_bf16 v[16:19], v[222:225], v[198:201], v[16:19]
	v_mfma_f32_16x16x32_bf16 v[4:7], v[214:217], v[206:209], v[4:7]
	v_mfma_f32_16x16x32_bf16 v[0:3], v[222:225], v[206:209], v[0:3]
	v_mfma_f32_16x16x32_bf16 v[52:55], v[218:221], v[184:187], v[52:55]
	v_mfma_f32_16x16x32_bf16 v[48:51], v[226:229], v[184:187], v[48:51]
	v_mfma_f32_16x16x32_bf16 v[36:39], v[218:221], v[194:197], v[36:39]
	v_mfma_f32_16x16x32_bf16 v[32:35], v[226:229], v[194:197], v[32:35]
	v_mfma_f32_16x16x32_bf16 v[20:23], v[218:221], v[202:205], v[20:23]
	v_mfma_f32_16x16x32_bf16 v[16:19], v[226:229], v[202:205], v[16:19]
	v_mfma_f32_16x16x32_bf16 v[4:7], v[218:221], v[210:213], v[4:7]
	v_mfma_f32_16x16x32_bf16 v[0:3], v[226:229], v[210:213], v[0:3]
	s_setprio 0
	s_add_i32 s52, s52, 2
	s_add_u32 s50, s50, 0x100
	s_addc_u32 s51, s51, 0
	s_cmp_gt_u32 s52, 21
	s_mov_b64 s[18:19], s[22:23]
	s_barrier
	s_cbranch_scc0 .LBB0_924
	s_lshl_b32 s22, s49, 8
	s_lshl_b32 s18, s48, 8
	v_add_u32_e32 v162, s22, v143
	s_ashr_i32 s19, s18, 31
	v_ashrrev_i32_e32 v163, 31, v162
	v_mov_b32_e32 v141, s19
	v_or_b32_e32 v140, s18, v134
	v_lshlrev_b64 v[162:163], 10, v[162:163]
	v_lshl_add_u64 v[162:163], v[140:141], 0, v[162:163]
	v_lshlrev_b64 v[164:165], 1, v[162:163]
	v_lshl_add_u64 v[162:163], s[20:21], 0, v[164:165]
	v_or_b32_e32 v168, 32, v164
	v_mov_b32_e32 v169, v165
	v_add_u32_e32 v230, s22, v143
	v_ashrrev_i32_e32 v231, 31, v230
	v_lshlrev_b64 v[230:231], 10, v[230:231]
	v_lshl_add_u64 v[230:231], v[140:141], 0, v[230:231]
	v_lshlrev_b64 v[230:231], 1, v[230:231]
	v_lshl_add_u64 v[230:231], s[20:21], 0, v[230:231]
	global_load_dwordx2 v[194:195], v[230:231], off
	global_load_dwordx2 v[196:197], v[230:231], off offset:32
	global_load_dwordx2 v[198:199], v[230:231], off offset:256
	global_load_dwordx2 v[200:201], v[230:231], off offset:288
	v_add_u32_e32 v230, s22, v146
	v_ashrrev_i32_e32 v231, 31, v230
	v_lshlrev_b64 v[230:231], 10, v[230:231]
	v_lshl_add_u64 v[230:231], v[140:141], 0, v[230:231]
	v_lshlrev_b64 v[230:231], 1, v[230:231]
	v_lshl_add_u64 v[230:231], s[20:21], 0, v[230:231]
	global_load_dwordx2 v[202:203], v[230:231], off
	global_load_dwordx2 v[204:205], v[230:231], off offset:32
	global_load_dwordx2 v[206:207], v[230:231], off offset:256
	global_load_dwordx2 v[208:209], v[230:231], off offset:288
	v_add_u32_e32 v230, s22, v148
	v_ashrrev_i32_e32 v231, 31, v230
	v_lshlrev_b64 v[230:231], 10, v[230:231]
	v_lshl_add_u64 v[230:231], v[140:141], 0, v[230:231]
	v_lshlrev_b64 v[230:231], 1, v[230:231]
	v_lshl_add_u64 v[230:231], s[20:21], 0, v[230:231]
	global_load_dwordx2 v[210:211], v[230:231], off
	global_load_dwordx2 v[212:213], v[230:231], off offset:32
	global_load_dwordx2 v[214:215], v[230:231], off offset:256
	global_load_dwordx2 v[216:217], v[230:231], off offset:288
	v_add_u32_e32 v230, s22, v150
	v_ashrrev_i32_e32 v231, 31, v230
	v_lshlrev_b64 v[230:231], 10, v[230:231]
	v_lshl_add_u64 v[230:231], v[140:141], 0, v[230:231]
	v_lshlrev_b64 v[230:231], 1, v[230:231]
	v_lshl_add_u64 v[230:231], s[20:21], 0, v[230:231]
	global_load_dwordx2 v[218:219], v[230:231], off
	global_load_dwordx2 v[220:221], v[230:231], off offset:32
	global_load_dwordx2 v[222:223], v[230:231], off offset:256
	global_load_dwordx2 v[224:225], v[230:231], off offset:288
	s_waitcnt vmcnt(12)
; DI float bflo(unsigned u) { return __uint_as_float(u << 16); }
; DI float bfhi(unsigned u) { return __uint_as_float(u & 0xffff0000u); }
; __global__ void __launch_bounds__(512) hybrid_fwd(Params p) {
;     ...
;                       for (int m = 0; m < 4; ++m) { const int rl = ai * 128 + wr * 64 + m * 16 + fr; const size_t ro = (size_t)(pm * 256 + rl) * 1024 + pn * 256 + wc * 32 + 4 * fq;
;                           float ssq = 0.f;
; #pragma unroll
;                           for (int bj = 0; bj < 2; ++bj)
; #pragma unroll
;                               for (int n = 0; n < 2; ++n) { const size_t o = ro + bj * 128 + n * 16; const u32x2 xb = *(const u32x2*)(U + o);
;                                   const f32x4 v = (f32x4){bflo(xb[0]), bfhi(xb[0]), bflo(xb[1]), bfhi(xb[1])} + acc[ai][bj][m][n];
	v_lshlrev_b32_e32 v226, 16, v194
	v_and_b32_e32 v227, 0xffff0000, v194
	v_lshlrev_b32_e32 v228, 16, v195
	v_and_b32_e32 v229, 0xffff0000, v195
	v_pk_add_f32 v[124:125], v[124:125], v[226:227]
	v_pk_add_f32 v[126:127], v[126:127], v[228:229]
	v_lshlrev_b32_e32 v226, 16, v196
	v_and_b32_e32 v227, 0xffff0000, v196
	v_lshlrev_b32_e32 v228, 16, v197
	v_and_b32_e32 v229, 0xffff0000, v197
	v_pk_add_f32 v[120:121], v[120:121], v[226:227]
	v_pk_add_f32 v[122:123], v[122:123], v[228:229]
	v_lshlrev_b32_e32 v226, 16, v198
	v_and_b32_e32 v227, 0xffff0000, v198
	v_lshlrev_b32_e32 v228, 16, v199
	v_and_b32_e32 v229, 0xffff0000, v199
	v_pk_add_f32 v[116:117], v[116:117], v[226:227]
	v_pk_add_f32 v[118:119], v[118:119], v[228:229]
	v_lshlrev_b32_e32 v226, 16, v200
	v_and_b32_e32 v227, 0xffff0000, v200
	v_lshlrev_b32_e32 v228, 16, v201
	v_and_b32_e32 v229, 0xffff0000, v201
	v_pk_add_f32 v[112:113], v[112:113], v[226:227]
	v_pk_add_f32 v[114:115], v[114:115], v[228:229]
	v_add_u32_e32 v230, s22, v152
	v_ashrrev_i32_e32 v231, 31, v230
	v_lshlrev_b64 v[230:231], 10, v[230:231]
	v_lshl_add_u64 v[230:231], v[140:141], 0, v[230:231]
	v_lshlrev_b64 v[230:231], 1, v[230:231]
	v_lshl_add_u64 v[230:231], s[20:21], 0, v[230:231]
	global_load_dwordx2 v[194:195], v[230:231], off
	global_load_dwordx2 v[196:197], v[230:231], off offset:32
	global_load_dwordx2 v[198:199], v[230:231], off offset:256
	global_load_dwordx2 v[200:201], v[230:231], off offset:288
	s_waitcnt vmcnt(12)
	v_lshlrev_b32_e32 v226, 16, v202
	v_and_b32_e32 v227, 0xffff0000, v202
	v_lshlrev_b32_e32 v228, 16, v203
	v_and_b32_e32 v229, 0xffff0000, v203
	v_pk_add_f32 v[108:109], v[108:109], v[226:227]
	v_pk_add_f32 v[110:111], v[110:111], v[228:229]
	v_lshlrev_b32_e32 v226, 16, v204
	v_and_b32_e32 v227, 0xffff0000, v204
	v_lshlrev_b32_e32 v228, 16, v205
	v_and_b32_e32 v229, 0xffff0000, v205
	v_pk_add_f32 v[104:105], v[104:105], v[226:227]
	v_pk_add_f32 v[106:107], v[106:107], v[228:229]
	v_lshlrev_b32_e32 v226, 16, v206
	v_and_b32_e32 v227, 0xffff0000, v206
	v_lshlrev_b32_e32 v228, 16, v207
	v_and_b32_e32 v229, 0xffff0000, v207
	v_pk_add_f32 v[100:101], v[100:101], v[226:227]
	v_pk_add_f32 v[102:103], v[102:103], v[228:229]
	v_lshlrev_b32_e32 v226, 16, v208
	v_and_b32_e32 v227, 0xffff0000, v208
	v_lshlrev_b32_e32 v228, 16, v209
	v_and_b32_e32 v229, 0xffff0000, v209
	v_pk_add_f32 v[96:97], v[96:97], v[226:227]
	v_pk_add_f32 v[98:99], v[98:99], v[228:229]
	v_add_u32_e32 v230, s22, v154
	v_ashrrev_i32_e32 v231, 31, v230
	v_lshlrev_b64 v[230:231], 10, v[230:231]
	v_lshl_add_u64 v[230:231], v[140:141], 0, v[230:231]
	v_lshlrev_b64 v[230:231], 1, v[230:231]
	v_lshl_add_u64 v[230:231], s[20:21], 0, v[230:231]
	global_load_dwordx2 v[202:203], v[230:231], off
	global_load_dwordx2 v[204:205], v[230:231], off offset:32
	global_load_dwordx2 v[206:207], v[230:231], off offset:256
	global_load_dwordx2 v[208:209], v[230:231], off offset:288
	s_waitcnt vmcnt(12)
	v_lshlrev_b32_e32 v226, 16, v210
	v_and_b32_e32 v227, 0xffff0000, v210
	v_lshlrev_b32_e32 v228, 16, v211
	v_and_b32_e32 v229, 0xffff0000, v211
	v_pk_add_f32 v[92:93], v[92:93], v[226:227]
	v_pk_add_f32 v[94:95], v[94:95], v[228:229]
	v_lshlrev_b32_e32 v226, 16, v212
	v_and_b32_e32 v227, 0xffff0000, v212
	v_lshlrev_b32_e32 v228, 16, v213
	v_and_b32_e32 v229, 0xffff0000, v213
	v_pk_add_f32 v[88:89], v[88:89], v[226:227]
	v_pk_add_f32 v[90:91], v[90:91], v[228:229]
	v_lshlrev_b32_e32 v226, 16, v214
	v_and_b32_e32 v227, 0xffff0000, v214
	v_lshlrev_b32_e32 v228, 16, v215
	v_and_b32_e32 v229, 0xffff0000, v215
	v_pk_add_f32 v[84:85], v[84:85], v[226:227]
	v_pk_add_f32 v[86:87], v[86:87], v[228:229]
	v_lshlrev_b32_e32 v226, 16, v216
	v_and_b32_e32 v227, 0xffff0000, v216
	v_lshlrev_b32_e32 v228, 16, v217
	v_and_b32_e32 v229, 0xffff0000, v217
	v_pk_add_f32 v[80:81], v[80:81], v[226:227]
	v_pk_add_f32 v[82:83], v[82:83], v[228:229]
	v_add_u32_e32 v230, s22, v156
	v_ashrrev_i32_e32 v231, 31, v230
	v_lshlrev_b64 v[230:231], 10, v[230:231]
	v_lshl_add_u64 v[230:231], v[140:141], 0, v[230:231]
	v_lshlrev_b64 v[230:231], 1, v[230:231]
	v_lshl_add_u64 v[230:231], s[20:21], 0, v[230:231]
	global_load_dwordx2 v[210:211], v[230:231], off
	global_load_dwordx2 v[212:213], v[230:231], off offset:32
	global_load_dwordx2 v[214:215], v[230:231], off offset:256
	global_load_dwordx2 v[216:217], v[230:231], off offset:288
	s_waitcnt vmcnt(12)
	v_lshlrev_b32_e32 v226, 16, v218
	v_and_b32_e32 v227, 0xffff0000, v218
	v_lshlrev_b32_e32 v228, 16, v219
	v_and_b32_e32 v229, 0xffff0000, v219
	v_pk_add_f32 v[76:77], v[76:77], v[226:227]
	v_pk_add_f32 v[78:79], v[78:79], v[228:229]
	v_lshlrev_b32_e32 v226, 16, v220
	v_and_b32_e32 v227, 0xffff0000, v220
	v_lshlrev_b32_e32 v228, 16, v221
	v_and_b32_e32 v229, 0xffff0000, v221
	v_pk_add_f32 v[72:73], v[72:73], v[226:227]
	v_pk_add_f32 v[74:75], v[74:75], v[228:229]
	v_lshlrev_b32_e32 v226, 16, v222
	v_and_b32_e32 v227, 0xffff0000, v222
	v_lshlrev_b32_e32 v228, 16, v223
	v_and_b32_e32 v229, 0xffff0000, v223
	v_pk_add_f32 v[68:69], v[68:69], v[226:227]
	v_pk_add_f32 v[70:71], v[70:71], v[228:229]
	v_lshlrev_b32_e32 v226, 16, v224
	v_and_b32_e32 v227, 0xffff0000, v224
	v_lshlrev_b32_e32 v228, 16, v225
	v_and_b32_e32 v229, 0xffff0000, v225
	v_pk_add_f32 v[64:65], v[64:65], v[226:227]
	v_pk_add_f32 v[66:67], v[66:67], v[228:229]
	v_add_u32_e32 v230, s22, v158
	v_ashrrev_i32_e32 v231, 31, v230
	v_lshlrev_b64 v[230:231], 10, v[230:231]
	v_lshl_add_u64 v[230:231], v[140:141], 0, v[230:231]
	v_lshlrev_b64 v[230:231], 1, v[230:231]
	v_lshl_add_u64 v[230:231], s[20:21], 0, v[230:231]
	global_load_dwordx2 v[218:219], v[230:231], off
	global_load_dwordx2 v[220:221], v[230:231], off offset:32
	global_load_dwordx2 v[222:223], v[230:231], off offset:256
	global_load_dwordx2 v[224:225], v[230:231], off offset:288
	s_waitcnt vmcnt(12)
; DI unsigned pk2(float a, float b) { f32x2 v = {a, b}; bf2_t r = __builtin_convertvector(v, bf2_t); return __builtin_bit_cast(unsigned, r); }
; DI float bflo(unsigned u) { return __uint_as_float(u << 16); }
; DI float bfhi(unsigned u) { return __uint_as_float(u & 0xffff0000u); }
; __global__ void __launch_bounds__(512) hybrid_fwd(Params p) {
;     ...
;               [=](const f32x4 (&acc)[2][2][4][2], int pm, int pn, int wr, int wc, int fr, int fq) {
; #pragma unroll
;                   for (int ai = 0; ai < 2; ++ai)
; #pragma unroll
;                       for (int m = 0; m < 4; ++m) { const int rl = ai * 128 + wr * 64 + m * 16 + fr; const size_t ro = (size_t)(pm * 256 + rl) * 1024 + pn * 256 + wc * 32 + 4 * fq;
;                           float ssq = 0.f;
; #pragma unroll
;                           for (int bj = 0; bj < 2; ++bj)
; #pragma unroll
;                               for (int n = 0; n < 2; ++n) { const size_t o = ro + bj * 128 + n * 16; const u32x2 xb = *(const u32x2*)(U + o);
;                                   const f32x4 v = (f32x4){bflo(xb[0]), bfhi(xb[0]), bflo(xb[1]), bfhi(xb[1])} + acc[ai][bj][m][n];
;                                   u32x2 wv; wv[0] = pk2(v[0], v[1]); wv[1] = pk2(v[2], v[3]); *(u32x2*)(X2B + o) = wv;
;                                   ssq += v[0] * v[0] + v[1] * v[1] + v[2] * v[2] + v[3] * v[3]; }
;                           ssq += __shfl_xor(ssq, 16); ssq += __shfl_xor(ssq, 32);
;                           if (fq == 0) __hip_atomic_fetch_add((float*)(shm + 131072) + rl, ssq, __ATOMIC_RELAXED, __HIP_MEMORY_SCOPE_WORKGROUP); } }, vb, panel);
	v_lshlrev_b32_e32 v226, 16, v194
	v_and_b32_e32 v227, 0xffff0000, v194
	v_lshlrev_b32_e32 v228, 16, v195
	v_and_b32_e32 v229, 0xffff0000, v195
	v_pk_add_f32 v[60:61], v[60:61], v[226:227]
	v_pk_add_f32 v[62:63], v[62:63], v[228:229]
	v_lshlrev_b32_e32 v226, 16, v196
	v_and_b32_e32 v227, 0xffff0000, v196
	v_lshlrev_b32_e32 v228, 16, v197
	v_and_b32_e32 v229, 0xffff0000, v197
	v_pk_add_f32 v[56:57], v[56:57], v[226:227]
	v_pk_add_f32 v[58:59], v[58:59], v[228:229]
	v_lshlrev_b32_e32 v226, 16, v198
	v_and_b32_e32 v227, 0xffff0000, v198
	v_lshlrev_b32_e32 v228, 16, v199
	v_and_b32_e32 v229, 0xffff0000, v199
	v_pk_add_f32 v[52:53], v[52:53], v[226:227]
	v_pk_add_f32 v[54:55], v[54:55], v[228:229]
	v_lshlrev_b32_e32 v226, 16, v200
	v_and_b32_e32 v227, 0xffff0000, v200
	v_lshlrev_b32_e32 v228, 16, v201
	v_and_b32_e32 v229, 0xffff0000, v201
	v_pk_add_f32 v[48:49], v[48:49], v[226:227]
	v_pk_add_f32 v[50:51], v[50:51], v[228:229]
	s_waitcnt vmcnt(8)
	v_lshlrev_b32_e32 v226, 16, v202
	v_and_b32_e32 v227, 0xffff0000, v202
	v_lshlrev_b32_e32 v228, 16, v203
	v_and_b32_e32 v229, 0xffff0000, v203
	v_pk_add_f32 v[44:45], v[44:45], v[226:227]
	v_pk_add_f32 v[46:47], v[46:47], v[228:229]
	v_lshlrev_b32_e32 v226, 16, v204
	v_and_b32_e32 v227, 0xffff0000, v204
	v_lshlrev_b32_e32 v228, 16, v205
	v_and_b32_e32 v229, 0xffff0000, v205
	v_pk_add_f32 v[40:41], v[40:41], v[226:227]
	v_pk_add_f32 v[42:43], v[42:43], v[228:229]
	v_lshlrev_b32_e32 v226, 16, v206
	v_and_b32_e32 v227, 0xffff0000, v206
	v_lshlrev_b32_e32 v228, 16, v207
	v_and_b32_e32 v229, 0xffff0000, v207
	v_pk_add_f32 v[36:37], v[36:37], v[226:227]
	v_pk_add_f32 v[38:39], v[38:39], v[228:229]
	v_lshlrev_b32_e32 v226, 16, v208
	v_and_b32_e32 v227, 0xffff0000, v208
	v_lshlrev_b32_e32 v228, 16, v209
	v_and_b32_e32 v229, 0xffff0000, v209
	v_pk_add_f32 v[32:33], v[32:33], v[226:227]
	v_pk_add_f32 v[34:35], v[34:35], v[228:229]
	s_waitcnt vmcnt(4)
	v_lshlrev_b32_e32 v226, 16, v210
	v_and_b32_e32 v227, 0xffff0000, v210
	v_lshlrev_b32_e32 v228, 16, v211
	v_and_b32_e32 v229, 0xffff0000, v211
	v_pk_add_f32 v[28:29], v[28:29], v[226:227]
	v_pk_add_f32 v[30:31], v[30:31], v[228:229]
	v_lshlrev_b32_e32 v226, 16, v212
	v_and_b32_e32 v227, 0xffff0000, v212
	v_lshlrev_b32_e32 v228, 16, v213
	v_and_b32_e32 v229, 0xffff0000, v213
	v_pk_add_f32 v[24:25], v[24:25], v[226:227]
	v_pk_add_f32 v[26:27], v[26:27], v[228:229]
	v_lshlrev_b32_e32 v226, 16, v214
	v_and_b32_e32 v227, 0xffff0000, v214
	v_lshlrev_b32_e32 v228, 16, v215
	v_and_b32_e32 v229, 0xffff0000, v215
	v_pk_add_f32 v[20:21], v[20:21], v[226:227]
	v_pk_add_f32 v[22:23], v[22:23], v[228:229]
	v_lshlrev_b32_e32 v226, 16, v216
	v_and_b32_e32 v227, 0xffff0000, v216
	v_lshlrev_b32_e32 v228, 16, v217
	v_and_b32_e32 v229, 0xffff0000, v217
	v_pk_add_f32 v[16:17], v[16:17], v[226:227]
	v_pk_add_f32 v[18:19], v[18:19], v[228:229]
	s_waitcnt vmcnt(0)
	v_lshlrev_b32_e32 v226, 16, v218
	v_and_b32_e32 v227, 0xffff0000, v218
	v_lshlrev_b32_e32 v228, 16, v219
	v_and_b32_e32 v229, 0xffff0000, v219
	v_pk_add_f32 v[12:13], v[12:13], v[226:227]
	v_pk_add_f32 v[14:15], v[14:15], v[228:229]
	v_lshlrev_b32_e32 v226, 16, v220
	v_and_b32_e32 v227, 0xffff0000, v220
	v_lshlrev_b32_e32 v228, 16, v221
	v_and_b32_e32 v229, 0xffff0000, v221
	v_pk_add_f32 v[8:9], v[8:9], v[226:227]
	v_pk_add_f32 v[10:11], v[10:11], v[228:229]
	v_lshlrev_b32_e32 v226, 16, v222
	v_and_b32_e32 v227, 0xffff0000, v222
	v_lshlrev_b32_e32 v228, 16, v223
	v_and_b32_e32 v229, 0xffff0000, v223
	v_pk_add_f32 v[4:5], v[4:5], v[226:227]
	v_pk_add_f32 v[6:7], v[6:7], v[228:229]
	v_lshlrev_b32_e32 v226, 16, v224
	v_and_b32_e32 v227, 0xffff0000, v224
	v_lshlrev_b32_e32 v228, 16, v225
	v_and_b32_e32 v229, 0xffff0000, v225
	v_pk_add_f32 v[0:1], v[0:1], v[226:227]
	v_pk_add_f32 v[2:3], v[2:3], v[228:229]
	v_lshl_add_u64 v[162:163], s[20:21], 0, v[168:169]
	v_or_b32_e32 v172, 0x100, v164
	v_mov_b32_e32 v173, v165
	v_lshl_add_u64 v[162:163], s[20:21], 0, v[172:173]
	v_lshl_add_u64 v[178:179], s[58:59], 0, v[164:165]
	v_or_b32_e32 v164, 0x120, v164
	v_lshl_add_u64 v[162:163], s[20:21], 0, v[164:165]
	v_and_b32_e32 v162, 64, v174
	v_xor_b32_e32 v161, 16, v174
	v_add_u32_e32 v162, 64, v162
	v_xor_b32_e32 v163, 32, v174
	v_cmp_lt_i32_e32 vcc, v161, v162
	v_lshl_add_u64 v[168:169], s[58:59], 0, v[168:169]
	v_lshlrev_b32_e32 v182, 16, v166
	v_and_b32_e32 v183, 0xffff0000, v166
	v_lshlrev_b32_e32 v166, 16, v167
	v_and_b32_e32 v167, 0xffff0000, v167
	v_lshlrev_b32_e32 v166, 16, v170
	v_and_b32_e32 v167, 0xffff0000, v170
	v_lshlrev_b32_e32 v182, 16, v176
	v_and_b32_e32 v183, 0xffff0000, v176
	v_lshlrev_b32_e32 v184, 16, v180
	v_and_b32_e32 v185, 0xffff0000, v180
	v_cndmask_b32_e32 v161, v174, v161, vcc
	v_cmp_lt_i32_e32 vcc, v163, v162
	v_lshlrev_b32_e32 v170, 16, v171
	v_and_b32_e32 v171, 0xffff0000, v171
	v_cvt_pk_bf16_f32 v186, v124, v125
	v_mul_f32_e32 v125, v125, v125
	v_mov_b32_e32 v166, v112
	v_mov_b32_e32 v167, v113
	v_cvt_pk_bf16_f32 v112, v120, v121
	v_mul_f32_e32 v121, v121, v121
	v_cndmask_b32_e32 v163, v174, v163, vcc
	v_lshlrev_b32_e32 v176, 16, v177
	v_and_b32_e32 v177, 0xffff0000, v177
	v_fmac_f32_e32 v125, v124, v124
	v_mul_f32_e32 v124, v117, v117
	v_fmac_f32_e32 v121, v120, v120
	v_lshlrev_b32_e32 v162, 2, v161
	v_lshlrev_b32_e32 v161, 2, v163
	v_lshlrev_b32_e32 v180, 16, v181
	v_and_b32_e32 v181, 0xffff0000, v181
	v_mul_f32_e32 v163, v167, v167
	v_fmac_f32_e32 v125, v126, v126
	v_fmac_f32_e32 v124, v116, v116
	v_fmac_f32_e32 v121, v122, v122
	v_cvt_pk_bf16_f32 v113, v122, v123
	v_fmac_f32_e32 v163, v166, v166
	v_fmac_f32_e32 v125, v127, v127
	v_fmac_f32_e32 v124, v118, v118
	v_fmac_f32_e32 v121, v123, v123
	global_store_dwordx2 v[168:169], v[112:113], off
	v_fmac_f32_e32 v163, v114, v114
	v_fmac_f32_e32 v124, v119, v119
	v_add_f32_e32 v112, v125, v121
	v_add_f32_e32 v112, v112, v124
	v_fmac_f32_e32 v163, v115, v115
	v_add_f32_e32 v120, v112, v163
	ds_bpermute_b32 v121, v162, v120
	v_cvt_pk_bf16_f32 v112, v116, v117
	v_cvt_pk_bf16_f32 v113, v118, v119
	v_lshl_add_u64 v[116:117], s[58:59], 0, v[172:173]
	global_store_dwordx2 v[116:117], v[112:113], off
	s_waitcnt lgkmcnt(0)
	v_add_f32_e32 v112, v120, v121
	ds_bpermute_b32 v113, v161, v112
	v_cvt_pk_bf16_f32 v187, v126, v127
	v_cvt_pk_bf16_f32 v116, v166, v167
	v_cvt_pk_bf16_f32 v117, v114, v115
	v_lshl_add_u64 v[114:115], s[58:59], 0, v[164:165]
	global_store_dwordx2 v[178:179], v[186:187], off
	global_store_dwordx2 v[114:115], v[116:117], off
	s_and_saveexec_b64 s[18:19], s[0:1]
	s_cbranch_execz .LBB0_927
	s_waitcnt lgkmcnt(0)
	v_add_f32_e32 v112, v112, v113
	ds_add_f32 v145, v112
; DI unsigned pk2(float a, float b) { f32x2 v = {a, b}; bf2_t r = __builtin_convertvector(v, bf2_t); return __builtin_bit_cast(unsigned, r); }
; DI float bflo(unsigned u) { return __uint_as_float(u << 16); }
; DI float bfhi(unsigned u) { return __uint_as_float(u & 0xffff0000u); }
; __global__ void __launch_bounds__(512) hybrid_fwd(Params p) {
;     ...
;                       for (int m = 0; m < 4; ++m) { const int rl = ai * 128 + wr * 64 + m * 16 + fr; const size_t ro = (size_t)(pm * 256 + rl) * 1024 + pn * 256 + wc * 32 + 4 * fq;
;                           float ssq = 0.f;
; #pragma unroll
;                           for (int bj = 0; bj < 2; ++bj)
; #pragma unroll
;                               for (int n = 0; n < 2; ++n) { const size_t o = ro + bj * 128 + n * 16; const u32x2 xb = *(const u32x2*)(U + o);
;                                   const f32x4 v = (f32x4){bflo(xb[0]), bfhi(xb[0]), bflo(xb[1]), bfhi(xb[1])} + acc[ai][bj][m][n];
;                                   u32x2 wv; wv[0] = pk2(v[0], v[1]); wv[1] = pk2(v[2], v[3]); *(u32x2*)(X2B + o) = wv;
;                                   ssq += v[0] * v[0] + v[1] * v[1] + v[2] * v[2] + v[3] * v[3]; }
;                           ssq += __shfl_xor(ssq, 16); ssq += __shfl_xor(ssq, 32);
;                           if (fq == 0) __hip_atomic_fetch_add((float*)(shm + 131072) + rl, ssq, __ATOMIC_RELAXED, __HIP_MEMORY_SCOPE_WORKGROUP); } }, vb, panel);
.LBB0_927:
	s_or_b64 exec, exec, s[18:19]
	v_add_u32_e32 v112, s22, v146
	s_waitcnt lgkmcnt(0)
	v_ashrrev_i32_e32 v113, 31, v112
	v_lshlrev_b64 v[112:113], 10, v[112:113]
	v_lshl_add_u64 v[112:113], v[140:141], 0, v[112:113]
	v_lshlrev_b64 v[112:113], 1, v[112:113]
	v_lshl_add_u64 v[114:115], s[20:21], 0, v[112:113]
	v_or_b32_e32 v116, 32, v112
	v_mov_b32_e32 v117, v113
	v_lshl_add_u64 v[118:119], s[20:21], 0, v[116:117]
	v_or_b32_e32 v120, 0x100, v112
	v_mov_b32_e32 v121, v113
	v_lshl_add_u64 v[124:125], s[58:59], 0, v[112:113]
	v_or_b32_e32 v112, 0x120, v112
	v_lshl_add_u64 v[122:123], s[20:21], 0, v[120:121]
	v_lshl_add_u64 v[126:127], s[20:21], 0, v[112:113]
	v_lshl_add_u64 v[116:117], s[58:59], 0, v[116:117]
	v_lshlrev_b32_e32 v164, 16, v114
	v_and_b32_e32 v165, 0xffff0000, v114
	v_lshlrev_b32_e32 v114, 16, v115
	v_and_b32_e32 v115, 0xffff0000, v115
	v_lshlrev_b32_e32 v114, 16, v118
	v_and_b32_e32 v115, 0xffff0000, v118
	v_lshlrev_b32_e32 v164, 16, v122
	v_and_b32_e32 v165, 0xffff0000, v122
	v_lshlrev_b32_e32 v166, 16, v126
	v_and_b32_e32 v167, 0xffff0000, v126
	v_lshlrev_b32_e32 v118, 16, v119
	v_and_b32_e32 v119, 0xffff0000, v119
	v_cvt_pk_bf16_f32 v168, v108, v109
	v_mul_f32_e32 v109, v109, v109
	v_mov_b32_e32 v114, v96
	v_mov_b32_e32 v115, v97
	v_cvt_pk_bf16_f32 v96, v104, v105
	v_mul_f32_e32 v105, v105, v105
	v_lshlrev_b32_e32 v122, 16, v123
	v_and_b32_e32 v123, 0xffff0000, v123
	v_fmac_f32_e32 v109, v108, v108
	v_mul_f32_e32 v108, v101, v101
	v_fmac_f32_e32 v105, v104, v104
	v_lshlrev_b32_e32 v126, 16, v127
	v_and_b32_e32 v127, 0xffff0000, v127
	v_mul_f32_e32 v118, v115, v115
	v_fmac_f32_e32 v109, v110, v110
	v_fmac_f32_e32 v108, v100, v100
	v_fmac_f32_e32 v105, v106, v106
	v_cvt_pk_bf16_f32 v97, v106, v107
	v_fmac_f32_e32 v118, v114, v114
	v_fmac_f32_e32 v109, v111, v111
	v_fmac_f32_e32 v108, v102, v102
	v_fmac_f32_e32 v105, v107, v107
	global_store_dwordx2 v[116:117], v[96:97], off
	v_fmac_f32_e32 v118, v98, v98
	v_fmac_f32_e32 v108, v103, v103
	v_add_f32_e32 v96, v109, v105
	v_add_f32_e32 v96, v96, v108
	v_fmac_f32_e32 v118, v99, v99
	v_add_f32_e32 v104, v96, v118
	ds_bpermute_b32 v105, v162, v104
	v_cvt_pk_bf16_f32 v96, v100, v101
	v_cvt_pk_bf16_f32 v97, v102, v103
	v_lshl_add_u64 v[100:101], s[58:59], 0, v[120:121]
	global_store_dwordx2 v[100:101], v[96:97], off
	s_waitcnt lgkmcnt(0)
	v_add_f32_e32 v96, v104, v105
	ds_bpermute_b32 v97, v161, v96
	v_cvt_pk_bf16_f32 v169, v110, v111
	v_cvt_pk_bf16_f32 v100, v114, v115
	v_cvt_pk_bf16_f32 v101, v98, v99
	v_lshl_add_u64 v[98:99], s[58:59], 0, v[112:113]
	global_store_dwordx2 v[124:125], v[168:169], off
	global_store_dwordx2 v[98:99], v[100:101], off
	s_and_saveexec_b64 s[18:19], s[0:1]
	s_cbranch_execz .LBB0_929
	s_waitcnt lgkmcnt(0)
	v_add_f32_e32 v96, v96, v97
	ds_add_f32 v147, v96
.LBB0_929:
	s_or_b64 exec, exec, s[18:19]
	v_add_u32_e32 v96, s22, v148
	s_waitcnt lgkmcnt(0)
	v_ashrrev_i32_e32 v97, 31, v96
	v_lshlrev_b64 v[96:97], 10, v[96:97]
	v_lshl_add_u64 v[96:97], v[140:141], 0, v[96:97]
	v_lshlrev_b64 v[96:97], 1, v[96:97]
	v_lshl_add_u64 v[98:99], s[20:21], 0, v[96:97]
	v_or_b32_e32 v100, 32, v96
	v_mov_b32_e32 v101, v97
	v_lshl_add_u64 v[102:103], s[20:21], 0, v[100:101]
	v_or_b32_e32 v104, 0x100, v96
	v_mov_b32_e32 v105, v97
	v_lshl_add_u64 v[108:109], s[58:59], 0, v[96:97]
	v_or_b32_e32 v96, 0x120, v96
	v_lshl_add_u64 v[106:107], s[20:21], 0, v[104:105]
	v_lshl_add_u64 v[110:111], s[20:21], 0, v[96:97]
	v_lshl_add_u64 v[100:101], s[58:59], 0, v[100:101]
	v_lshlrev_b32_e32 v112, 16, v98
	v_and_b32_e32 v113, 0xffff0000, v98
	v_lshlrev_b32_e32 v98, 16, v99
	v_and_b32_e32 v99, 0xffff0000, v99
	v_lshlrev_b32_e32 v98, 16, v102
	v_and_b32_e32 v99, 0xffff0000, v102
	v_lshlrev_b32_e32 v112, 16, v106
	v_and_b32_e32 v113, 0xffff0000, v106
	v_lshlrev_b32_e32 v114, 16, v110
	v_and_b32_e32 v115, 0xffff0000, v110
	v_lshlrev_b32_e32 v102, 16, v103
	v_and_b32_e32 v103, 0xffff0000, v103
	v_cvt_pk_bf16_f32 v116, v92, v93
	v_mul_f32_e32 v93, v93, v93
	v_mov_b32_e32 v98, v80
	v_mov_b32_e32 v99, v81
	v_cvt_pk_bf16_f32 v80, v88, v89
	v_mul_f32_e32 v89, v89, v89
	v_lshlrev_b32_e32 v106, 16, v107
	v_and_b32_e32 v107, 0xffff0000, v107
	v_fmac_f32_e32 v93, v92, v92
	v_mul_f32_e32 v92, v85, v85
	v_fmac_f32_e32 v89, v88, v88
	v_lshlrev_b32_e32 v110, 16, v111
	v_and_b32_e32 v111, 0xffff0000, v111
	v_mul_f32_e32 v102, v99, v99
	v_fmac_f32_e32 v93, v94, v94
	v_fmac_f32_e32 v92, v84, v84
	v_fmac_f32_e32 v89, v90, v90
	v_cvt_pk_bf16_f32 v81, v90, v91
	v_fmac_f32_e32 v102, v98, v98
	v_fmac_f32_e32 v93, v95, v95
	v_fmac_f32_e32 v92, v86, v86
	v_fmac_f32_e32 v89, v91, v91
	global_store_dwordx2 v[100:101], v[80:81], off
	v_fmac_f32_e32 v102, v82, v82
	v_fmac_f32_e32 v92, v87, v87
	v_add_f32_e32 v80, v93, v89
	v_add_f32_e32 v80, v80, v92
	v_fmac_f32_e32 v102, v83, v83
	v_add_f32_e32 v88, v80, v102
	ds_bpermute_b32 v89, v162, v88
	v_cvt_pk_bf16_f32 v80, v84, v85
	v_cvt_pk_bf16_f32 v81, v86, v87
	v_lshl_add_u64 v[84:85], s[58:59], 0, v[104:105]
	global_store_dwordx2 v[84:85], v[80:81], off
	s_waitcnt lgkmcnt(0)
	v_add_f32_e32 v80, v88, v89
	ds_bpermute_b32 v81, v161, v80
	v_cvt_pk_bf16_f32 v117, v94, v95
	v_cvt_pk_bf16_f32 v84, v98, v99
	v_cvt_pk_bf16_f32 v85, v82, v83
	v_lshl_add_u64 v[82:83], s[58:59], 0, v[96:97]
	global_store_dwordx2 v[108:109], v[116:117], off
	global_store_dwordx2 v[82:83], v[84:85], off
	s_and_saveexec_b64 s[18:19], s[0:1]
	s_cbranch_execz .LBB0_931
	s_waitcnt lgkmcnt(0)
	v_add_f32_e32 v80, v80, v81
	ds_add_f32 v149, v80
; DI unsigned pk2(float a, float b) { f32x2 v = {a, b}; bf2_t r = __builtin_convertvector(v, bf2_t); return __builtin_bit_cast(unsigned, r); }
; DI float bflo(unsigned u) { return __uint_as_float(u << 16); }
; DI float bfhi(unsigned u) { return __uint_as_float(u & 0xffff0000u); }
; __global__ void __launch_bounds__(512) hybrid_fwd(Params p) {
;     ...
;                       for (int m = 0; m < 4; ++m) { const int rl = ai * 128 + wr * 64 + m * 16 + fr; const size_t ro = (size_t)(pm * 256 + rl) * 1024 + pn * 256 + wc * 32 + 4 * fq;
;                           float ssq = 0.f;
; #pragma unroll
;                           for (int bj = 0; bj < 2; ++bj)
; #pragma unroll
;                               for (int n = 0; n < 2; ++n) { const size_t o = ro + bj * 128 + n * 16; const u32x2 xb = *(const u32x2*)(U + o);
;                                   const f32x4 v = (f32x4){bflo(xb[0]), bfhi(xb[0]), bflo(xb[1]), bfhi(xb[1])} + acc[ai][bj][m][n];
;                                   u32x2 wv; wv[0] = pk2(v[0], v[1]); wv[1] = pk2(v[2], v[3]); *(u32x2*)(X2B + o) = wv;
;                                   ssq += v[0] * v[0] + v[1] * v[1] + v[2] * v[2] + v[3] * v[3]; }
;                           ssq += __shfl_xor(ssq, 16); ssq += __shfl_xor(ssq, 32);
;                           if (fq == 0) __hip_atomic_fetch_add((float*)(shm + 131072) + rl, ssq, __ATOMIC_RELAXED, __HIP_MEMORY_SCOPE_WORKGROUP); } }, vb, panel);
.LBB0_931:
	s_or_b64 exec, exec, s[18:19]
	v_add_u32_e32 v80, s22, v150
	s_waitcnt lgkmcnt(0)
	v_ashrrev_i32_e32 v81, 31, v80
	v_lshlrev_b64 v[80:81], 10, v[80:81]
	v_lshl_add_u64 v[80:81], v[140:141], 0, v[80:81]
	v_lshlrev_b64 v[80:81], 1, v[80:81]
	v_lshl_add_u64 v[82:83], s[20:21], 0, v[80:81]
	v_or_b32_e32 v84, 32, v80
	v_mov_b32_e32 v85, v81
	v_lshl_add_u64 v[86:87], s[20:21], 0, v[84:85]
	v_or_b32_e32 v88, 0x100, v80
	v_mov_b32_e32 v89, v81
	v_lshl_add_u64 v[92:93], s[58:59], 0, v[80:81]
	v_or_b32_e32 v80, 0x120, v80
	v_lshl_add_u64 v[90:91], s[20:21], 0, v[88:89]
	v_lshl_add_u64 v[94:95], s[20:21], 0, v[80:81]
	v_lshl_add_u64 v[84:85], s[58:59], 0, v[84:85]
	v_lshlrev_b32_e32 v96, 16, v82
	v_and_b32_e32 v97, 0xffff0000, v82
	v_lshlrev_b32_e32 v82, 16, v83
	v_and_b32_e32 v83, 0xffff0000, v83
	v_lshlrev_b32_e32 v82, 16, v86
	v_and_b32_e32 v83, 0xffff0000, v86
	v_lshlrev_b32_e32 v96, 16, v90
	v_and_b32_e32 v97, 0xffff0000, v90
	v_lshlrev_b32_e32 v98, 16, v94
	v_and_b32_e32 v99, 0xffff0000, v94
	v_lshlrev_b32_e32 v86, 16, v87
	v_and_b32_e32 v87, 0xffff0000, v87
	v_cvt_pk_bf16_f32 v100, v76, v77
	v_mul_f32_e32 v77, v77, v77
	v_mov_b32_e32 v82, v64
	v_mov_b32_e32 v83, v65
	v_cvt_pk_bf16_f32 v64, v72, v73
	v_mul_f32_e32 v73, v73, v73
	v_lshlrev_b32_e32 v90, 16, v91
	v_and_b32_e32 v91, 0xffff0000, v91
	v_fmac_f32_e32 v77, v76, v76
	v_mul_f32_e32 v76, v69, v69
	v_fmac_f32_e32 v73, v72, v72
	v_lshlrev_b32_e32 v94, 16, v95
	v_and_b32_e32 v95, 0xffff0000, v95
	v_mul_f32_e32 v86, v83, v83
	v_fmac_f32_e32 v77, v78, v78
	v_fmac_f32_e32 v76, v68, v68
	v_fmac_f32_e32 v73, v74, v74
	v_cvt_pk_bf16_f32 v65, v74, v75
	v_fmac_f32_e32 v86, v82, v82
	v_fmac_f32_e32 v77, v79, v79
	v_fmac_f32_e32 v76, v70, v70
	v_fmac_f32_e32 v73, v75, v75
	global_store_dwordx2 v[84:85], v[64:65], off
	v_fmac_f32_e32 v86, v66, v66
	v_fmac_f32_e32 v76, v71, v71
	v_add_f32_e32 v64, v77, v73
	v_add_f32_e32 v64, v64, v76
	v_fmac_f32_e32 v86, v67, v67
	v_add_f32_e32 v72, v64, v86
	ds_bpermute_b32 v73, v162, v72
	v_cvt_pk_bf16_f32 v64, v68, v69
	v_cvt_pk_bf16_f32 v65, v70, v71
	v_lshl_add_u64 v[68:69], s[58:59], 0, v[88:89]
	global_store_dwordx2 v[68:69], v[64:65], off
	s_waitcnt lgkmcnt(0)
	v_add_f32_e32 v64, v72, v73
	ds_bpermute_b32 v65, v161, v64
	v_cvt_pk_bf16_f32 v101, v78, v79
	v_cvt_pk_bf16_f32 v68, v82, v83
	v_cvt_pk_bf16_f32 v69, v66, v67
	v_lshl_add_u64 v[66:67], s[58:59], 0, v[80:81]
	global_store_dwordx2 v[92:93], v[100:101], off
	global_store_dwordx2 v[66:67], v[68:69], off
	s_and_saveexec_b64 s[18:19], s[0:1]
	s_cbranch_execz .LBB0_933
	s_waitcnt lgkmcnt(0)
	v_add_f32_e32 v64, v64, v65
	ds_add_f32 v151, v64
.LBB0_933:
	s_or_b64 exec, exec, s[18:19]
	v_add_u32_e32 v64, s22, v152
	s_waitcnt lgkmcnt(0)
	v_ashrrev_i32_e32 v65, 31, v64
	v_lshlrev_b64 v[64:65], 10, v[64:65]
	v_lshl_add_u64 v[64:65], v[140:141], 0, v[64:65]
	v_lshlrev_b64 v[64:65], 1, v[64:65]
	v_lshl_add_u64 v[66:67], s[20:21], 0, v[64:65]
	v_or_b32_e32 v68, 32, v64
	v_mov_b32_e32 v69, v65
	v_lshl_add_u64 v[70:71], s[20:21], 0, v[68:69]
	v_or_b32_e32 v72, 0x100, v64
	v_mov_b32_e32 v73, v65
	v_lshl_add_u64 v[76:77], s[58:59], 0, v[64:65]
	v_or_b32_e32 v64, 0x120, v64
	v_lshl_add_u64 v[74:75], s[20:21], 0, v[72:73]
	v_lshl_add_u64 v[78:79], s[20:21], 0, v[64:65]
	v_lshl_add_u64 v[68:69], s[58:59], 0, v[68:69]
	v_lshlrev_b32_e32 v80, 16, v66
	v_and_b32_e32 v81, 0xffff0000, v66
	v_lshlrev_b32_e32 v66, 16, v67
	v_and_b32_e32 v67, 0xffff0000, v67
	v_lshlrev_b32_e32 v66, 16, v70
	v_and_b32_e32 v67, 0xffff0000, v70
	v_lshlrev_b32_e32 v80, 16, v74
	v_and_b32_e32 v81, 0xffff0000, v74
	v_lshlrev_b32_e32 v82, 16, v78
	v_and_b32_e32 v83, 0xffff0000, v78
	v_lshlrev_b32_e32 v70, 16, v71
	v_and_b32_e32 v71, 0xffff0000, v71
	v_cvt_pk_bf16_f32 v84, v60, v61
	v_mul_f32_e32 v61, v61, v61
	v_mov_b32_e32 v66, v48
	v_mov_b32_e32 v67, v49
	v_cvt_pk_bf16_f32 v48, v56, v57
	v_mul_f32_e32 v57, v57, v57
	v_lshlrev_b32_e32 v74, 16, v75
	v_and_b32_e32 v75, 0xffff0000, v75
	v_fmac_f32_e32 v61, v60, v60
	v_mul_f32_e32 v60, v53, v53
	v_fmac_f32_e32 v57, v56, v56
	v_lshlrev_b32_e32 v78, 16, v79
	v_and_b32_e32 v79, 0xffff0000, v79
	v_mul_f32_e32 v70, v67, v67
	v_fmac_f32_e32 v61, v62, v62
	v_fmac_f32_e32 v60, v52, v52
	v_fmac_f32_e32 v57, v58, v58
	v_cvt_pk_bf16_f32 v49, v58, v59
	v_fmac_f32_e32 v70, v66, v66
	v_fmac_f32_e32 v61, v63, v63
	v_fmac_f32_e32 v60, v54, v54
	v_fmac_f32_e32 v57, v59, v59
	global_store_dwordx2 v[68:69], v[48:49], off
	v_fmac_f32_e32 v70, v50, v50
	v_fmac_f32_e32 v60, v55, v55
	v_add_f32_e32 v48, v61, v57
	v_add_f32_e32 v48, v48, v60
	v_fmac_f32_e32 v70, v51, v51
	v_add_f32_e32 v56, v48, v70
	ds_bpermute_b32 v57, v162, v56
	v_cvt_pk_bf16_f32 v48, v52, v53
	v_cvt_pk_bf16_f32 v49, v54, v55
	v_lshl_add_u64 v[52:53], s[58:59], 0, v[72:73]
	global_store_dwordx2 v[52:53], v[48:49], off
	s_waitcnt lgkmcnt(0)
	v_add_f32_e32 v48, v56, v57
	ds_bpermute_b32 v49, v161, v48
	v_cvt_pk_bf16_f32 v85, v62, v63
	v_cvt_pk_bf16_f32 v52, v66, v67
	v_cvt_pk_bf16_f32 v53, v50, v51
	v_lshl_add_u64 v[50:51], s[58:59], 0, v[64:65]
	global_store_dwordx2 v[76:77], v[84:85], off
	global_store_dwordx2 v[50:51], v[52:53], off
	s_and_saveexec_b64 s[18:19], s[0:1]
	s_cbranch_execz .LBB0_935
	s_waitcnt lgkmcnt(0)
	v_add_f32_e32 v48, v48, v49
	ds_add_f32 v153, v48
; DI unsigned pk2(float a, float b) { f32x2 v = {a, b}; bf2_t r = __builtin_convertvector(v, bf2_t); return __builtin_bit_cast(unsigned, r); }
; DI float bflo(unsigned u) { return __uint_as_float(u << 16); }
; DI float bfhi(unsigned u) { return __uint_as_float(u & 0xffff0000u); }
; __global__ void __launch_bounds__(512) hybrid_fwd(Params p) {
;     ...
;                       for (int m = 0; m < 4; ++m) { const int rl = ai * 128 + wr * 64 + m * 16 + fr; const size_t ro = (size_t)(pm * 256 + rl) * 1024 + pn * 256 + wc * 32 + 4 * fq;
;                           float ssq = 0.f;
; #pragma unroll
;                           for (int bj = 0; bj < 2; ++bj)
; #pragma unroll
;                               for (int n = 0; n < 2; ++n) { const size_t o = ro + bj * 128 + n * 16; const u32x2 xb = *(const u32x2*)(U + o);
;                                   const f32x4 v = (f32x4){bflo(xb[0]), bfhi(xb[0]), bflo(xb[1]), bfhi(xb[1])} + acc[ai][bj][m][n];
;                                   u32x2 wv; wv[0] = pk2(v[0], v[1]); wv[1] = pk2(v[2], v[3]); *(u32x2*)(X2B + o) = wv;
;                                   ssq += v[0] * v[0] + v[1] * v[1] + v[2] * v[2] + v[3] * v[3]; }
;                           ssq += __shfl_xor(ssq, 16); ssq += __shfl_xor(ssq, 32);
;                           if (fq == 0) __hip_atomic_fetch_add((float*)(shm + 131072) + rl, ssq, __ATOMIC_RELAXED, __HIP_MEMORY_SCOPE_WORKGROUP); } }, vb, panel);
.LBB0_935:
	s_or_b64 exec, exec, s[18:19]
	v_add_u32_e32 v48, s22, v154
	s_waitcnt lgkmcnt(0)
	v_ashrrev_i32_e32 v49, 31, v48
	v_lshlrev_b64 v[48:49], 10, v[48:49]
	v_lshl_add_u64 v[48:49], v[140:141], 0, v[48:49]
	v_lshlrev_b64 v[48:49], 1, v[48:49]
	v_lshl_add_u64 v[50:51], s[20:21], 0, v[48:49]
	v_or_b32_e32 v52, 32, v48
	v_mov_b32_e32 v53, v49
	v_lshl_add_u64 v[54:55], s[20:21], 0, v[52:53]
	v_or_b32_e32 v56, 0x100, v48
	v_mov_b32_e32 v57, v49
	v_lshl_add_u64 v[60:61], s[58:59], 0, v[48:49]
	v_or_b32_e32 v48, 0x120, v48
	v_lshl_add_u64 v[58:59], s[20:21], 0, v[56:57]
	v_lshl_add_u64 v[62:63], s[20:21], 0, v[48:49]
	v_lshl_add_u64 v[52:53], s[58:59], 0, v[52:53]
	v_lshlrev_b32_e32 v64, 16, v50
	v_and_b32_e32 v65, 0xffff0000, v50
	v_lshlrev_b32_e32 v50, 16, v51
	v_and_b32_e32 v51, 0xffff0000, v51
	v_lshlrev_b32_e32 v50, 16, v54
	v_and_b32_e32 v51, 0xffff0000, v54
	v_lshlrev_b32_e32 v64, 16, v58
	v_and_b32_e32 v65, 0xffff0000, v58
	v_lshlrev_b32_e32 v66, 16, v62
	v_and_b32_e32 v67, 0xffff0000, v62
	v_lshlrev_b32_e32 v54, 16, v55
	v_and_b32_e32 v55, 0xffff0000, v55
	v_cvt_pk_bf16_f32 v68, v44, v45
	v_mul_f32_e32 v45, v45, v45
	v_mov_b32_e32 v50, v32
	v_mov_b32_e32 v51, v33
	v_cvt_pk_bf16_f32 v32, v40, v41
	v_mul_f32_e32 v41, v41, v41
	v_lshlrev_b32_e32 v58, 16, v59
	v_and_b32_e32 v59, 0xffff0000, v59
	v_fmac_f32_e32 v45, v44, v44
	v_mul_f32_e32 v44, v37, v37
	v_fmac_f32_e32 v41, v40, v40
	v_lshlrev_b32_e32 v62, 16, v63
	v_and_b32_e32 v63, 0xffff0000, v63
	v_mul_f32_e32 v54, v51, v51
	v_fmac_f32_e32 v45, v46, v46
	v_fmac_f32_e32 v44, v36, v36
	v_fmac_f32_e32 v41, v42, v42
	v_cvt_pk_bf16_f32 v33, v42, v43
	v_fmac_f32_e32 v54, v50, v50
	v_fmac_f32_e32 v45, v47, v47
	v_fmac_f32_e32 v44, v38, v38
	v_fmac_f32_e32 v41, v43, v43
	global_store_dwordx2 v[52:53], v[32:33], off
	v_fmac_f32_e32 v54, v34, v34
	v_fmac_f32_e32 v44, v39, v39
	v_add_f32_e32 v32, v45, v41
	v_add_f32_e32 v32, v32, v44
	v_fmac_f32_e32 v54, v35, v35
	v_add_f32_e32 v40, v32, v54
	ds_bpermute_b32 v41, v162, v40
	v_cvt_pk_bf16_f32 v32, v36, v37
	v_cvt_pk_bf16_f32 v33, v38, v39
	v_lshl_add_u64 v[36:37], s[58:59], 0, v[56:57]
	global_store_dwordx2 v[36:37], v[32:33], off
	s_waitcnt lgkmcnt(0)
	v_add_f32_e32 v32, v40, v41
	ds_bpermute_b32 v33, v161, v32
	v_cvt_pk_bf16_f32 v69, v46, v47
	v_cvt_pk_bf16_f32 v36, v50, v51
	v_cvt_pk_bf16_f32 v37, v34, v35
	v_lshl_add_u64 v[34:35], s[58:59], 0, v[48:49]
	global_store_dwordx2 v[60:61], v[68:69], off
	global_store_dwordx2 v[34:35], v[36:37], off
	s_and_saveexec_b64 s[18:19], s[0:1]
	s_cbranch_execz .LBB0_937
	s_waitcnt lgkmcnt(0)
	v_add_f32_e32 v32, v32, v33
	ds_add_f32 v155, v32
; DI unsigned pk2(float a, float b) { f32x2 v = {a, b}; bf2_t r = __builtin_convertvector(v, bf2_t); return __builtin_bit_cast(unsigned, r); }
; DI float bflo(unsigned u) { return __uint_as_float(u << 16); }
; DI float bfhi(unsigned u) { return __uint_as_float(u & 0xffff0000u); }
; __global__ void __launch_bounds__(512) hybrid_fwd(Params p) {
;     ...
;                       for (int m = 0; m < 4; ++m) { const int rl = ai * 128 + wr * 64 + m * 16 + fr; const size_t ro = (size_t)(pm * 256 + rl) * 1024 + pn * 256 + wc * 32 + 4 * fq;
;                           float ssq = 0.f;
; #pragma unroll
;                           for (int bj = 0; bj < 2; ++bj)
; #pragma unroll
;                               for (int n = 0; n < 2; ++n) { const size_t o = ro + bj * 128 + n * 16; const u32x2 xb = *(const u32x2*)(U + o);
;                                   const f32x4 v = (f32x4){bflo(xb[0]), bfhi(xb[0]), bflo(xb[1]), bfhi(xb[1])} + acc[ai][bj][m][n];
;                                   u32x2 wv; wv[0] = pk2(v[0], v[1]); wv[1] = pk2(v[2], v[3]); *(u32x2*)(X2B + o) = wv;
;                                   ssq += v[0] * v[0] + v[1] * v[1] + v[2] * v[2] + v[3] * v[3]; }
;                           ssq += __shfl_xor(ssq, 16); ssq += __shfl_xor(ssq, 32);
;                           if (fq == 0) __hip_atomic_fetch_add((float*)(shm + 131072) + rl, ssq, __ATOMIC_RELAXED, __HIP_MEMORY_SCOPE_WORKGROUP); } }, vb, panel);
.LBB0_937:
	s_or_b64 exec, exec, s[18:19]
	v_add_u32_e32 v32, s22, v156
	s_waitcnt lgkmcnt(0)
	v_ashrrev_i32_e32 v33, 31, v32
	v_lshlrev_b64 v[32:33], 10, v[32:33]
	v_lshl_add_u64 v[32:33], v[140:141], 0, v[32:33]
	v_lshlrev_b64 v[32:33], 1, v[32:33]
	v_lshl_add_u64 v[34:35], s[20:21], 0, v[32:33]
	v_or_b32_e32 v36, 32, v32
	v_mov_b32_e32 v37, v33
	v_lshl_add_u64 v[38:39], s[20:21], 0, v[36:37]
	v_or_b32_e32 v40, 0x100, v32
	v_mov_b32_e32 v41, v33
	v_lshl_add_u64 v[44:45], s[58:59], 0, v[32:33]
	v_or_b32_e32 v32, 0x120, v32
	v_lshl_add_u64 v[42:43], s[20:21], 0, v[40:41]
	v_lshl_add_u64 v[46:47], s[20:21], 0, v[32:33]
	v_lshl_add_u64 v[36:37], s[58:59], 0, v[36:37]
	v_lshlrev_b32_e32 v48, 16, v34
	v_and_b32_e32 v49, 0xffff0000, v34
	v_lshlrev_b32_e32 v34, 16, v35
	v_and_b32_e32 v35, 0xffff0000, v35
	v_lshlrev_b32_e32 v34, 16, v38
	v_and_b32_e32 v35, 0xffff0000, v38
	v_lshlrev_b32_e32 v48, 16, v42
	v_and_b32_e32 v49, 0xffff0000, v42
	v_lshlrev_b32_e32 v50, 16, v46
	v_and_b32_e32 v51, 0xffff0000, v46
	v_lshlrev_b32_e32 v38, 16, v39
	v_and_b32_e32 v39, 0xffff0000, v39
	v_cvt_pk_bf16_f32 v52, v28, v29
	v_mul_f32_e32 v29, v29, v29
	v_mov_b32_e32 v34, v16
	v_mov_b32_e32 v35, v17
	v_cvt_pk_bf16_f32 v16, v24, v25
	v_mul_f32_e32 v25, v25, v25
	v_lshlrev_b32_e32 v42, 16, v43
	v_and_b32_e32 v43, 0xffff0000, v43
	v_fmac_f32_e32 v29, v28, v28
	v_mul_f32_e32 v28, v21, v21
	v_fmac_f32_e32 v25, v24, v24
	v_lshlrev_b32_e32 v46, 16, v47
	v_and_b32_e32 v47, 0xffff0000, v47
	v_mul_f32_e32 v38, v35, v35
	v_fmac_f32_e32 v29, v30, v30
	v_fmac_f32_e32 v28, v20, v20
	v_fmac_f32_e32 v25, v26, v26
	v_cvt_pk_bf16_f32 v17, v26, v27
	v_fmac_f32_e32 v38, v34, v34
	v_fmac_f32_e32 v29, v31, v31
	v_fmac_f32_e32 v28, v22, v22
	v_fmac_f32_e32 v25, v27, v27
	global_store_dwordx2 v[36:37], v[16:17], off
	v_fmac_f32_e32 v38, v18, v18
	v_fmac_f32_e32 v28, v23, v23
	v_add_f32_e32 v16, v29, v25
	v_add_f32_e32 v16, v16, v28
	v_fmac_f32_e32 v38, v19, v19
	v_add_f32_e32 v24, v16, v38
	ds_bpermute_b32 v25, v162, v24
	v_cvt_pk_bf16_f32 v16, v20, v21
	v_cvt_pk_bf16_f32 v17, v22, v23
	v_lshl_add_u64 v[20:21], s[58:59], 0, v[40:41]
	global_store_dwordx2 v[20:21], v[16:17], off
	s_waitcnt lgkmcnt(0)
	v_add_f32_e32 v16, v24, v25
	ds_bpermute_b32 v17, v161, v16
	v_cvt_pk_bf16_f32 v53, v30, v31
	v_cvt_pk_bf16_f32 v20, v34, v35
	v_cvt_pk_bf16_f32 v21, v18, v19
	v_lshl_add_u64 v[18:19], s[58:59], 0, v[32:33]
	global_store_dwordx2 v[44:45], v[52:53], off
	global_store_dwordx2 v[18:19], v[20:21], off
	s_and_saveexec_b64 s[18:19], s[0:1]
	s_cbranch_execz .LBB0_939
	s_waitcnt lgkmcnt(0)
	v_add_f32_e32 v16, v16, v17
	ds_add_f32 v157, v16
.LBB0_939:
	s_or_b64 exec, exec, s[18:19]
	v_add_u32_e32 v16, s22, v158
	s_waitcnt lgkmcnt(0)
	v_ashrrev_i32_e32 v17, 31, v16
	v_lshlrev_b64 v[16:17], 10, v[16:17]
	v_lshl_add_u64 v[16:17], v[140:141], 0, v[16:17]
	v_lshlrev_b64 v[16:17], 1, v[16:17]
	v_lshl_add_u64 v[18:19], s[20:21], 0, v[16:17]
	v_or_b32_e32 v20, 32, v16
	v_mov_b32_e32 v21, v17
	v_lshl_add_u64 v[22:23], s[20:21], 0, v[20:21]
	v_or_b32_e32 v24, 0x100, v16
	v_mov_b32_e32 v25, v17
	v_lshl_add_u64 v[28:29], s[58:59], 0, v[16:17]
	v_or_b32_e32 v16, 0x120, v16
	v_lshl_add_u64 v[26:27], s[20:21], 0, v[24:25]
	v_lshl_add_u64 v[30:31], s[20:21], 0, v[16:17]
	v_lshl_add_u64 v[20:21], s[58:59], 0, v[20:21]
	v_lshlrev_b32_e32 v32, 16, v18
	v_and_b32_e32 v33, 0xffff0000, v18
	v_lshlrev_b32_e32 v18, 16, v19
	v_and_b32_e32 v19, 0xffff0000, v19
	v_lshlrev_b32_e32 v18, 16, v22
	v_and_b32_e32 v19, 0xffff0000, v22
	v_lshlrev_b32_e32 v32, 16, v26
	v_and_b32_e32 v33, 0xffff0000, v26
	v_lshlrev_b32_e32 v34, 16, v30
	v_and_b32_e32 v35, 0xffff0000, v30
	v_lshlrev_b32_e32 v22, 16, v23
	v_and_b32_e32 v23, 0xffff0000, v23
	v_cvt_pk_bf16_f32 v36, v12, v13
	v_mul_f32_e32 v13, v13, v13
	v_mov_b32_e32 v18, v0
	v_mov_b32_e32 v19, v1
	v_cvt_pk_bf16_f32 v0, v8, v9
	v_mul_f32_e32 v9, v9, v9
	v_lshlrev_b32_e32 v26, 16, v27
	v_and_b32_e32 v27, 0xffff0000, v27
	v_fmac_f32_e32 v13, v12, v12
	v_mul_f32_e32 v12, v5, v5
	v_fmac_f32_e32 v9, v8, v8
	v_lshlrev_b32_e32 v30, 16, v31
	v_and_b32_e32 v31, 0xffff0000, v31
	v_mul_f32_e32 v22, v19, v19
	v_fmac_f32_e32 v13, v14, v14
	v_fmac_f32_e32 v12, v4, v4
	v_fmac_f32_e32 v9, v10, v10
	v_cvt_pk_bf16_f32 v1, v10, v11
	v_fmac_f32_e32 v22, v18, v18
	v_fmac_f32_e32 v13, v15, v15
	v_fmac_f32_e32 v12, v6, v6
	v_fmac_f32_e32 v9, v11, v11
	global_store_dwordx2 v[20:21], v[0:1], off
	v_fmac_f32_e32 v22, v2, v2
	v_fmac_f32_e32 v12, v7, v7
	v_add_f32_e32 v0, v13, v9
	v_add_f32_e32 v0, v0, v12
	v_fmac_f32_e32 v22, v3, v3
	v_add_f32_e32 v8, v0, v22
	ds_bpermute_b32 v9, v162, v8
	v_cvt_pk_bf16_f32 v0, v4, v5
	v_cvt_pk_bf16_f32 v1, v6, v7
	v_lshl_add_u64 v[4:5], s[58:59], 0, v[24:25]
	global_store_dwordx2 v[4:5], v[0:1], off
	s_waitcnt lgkmcnt(0)
	v_add_f32_e32 v0, v8, v9
	ds_bpermute_b32 v1, v161, v0
	v_cvt_pk_bf16_f32 v37, v14, v15
	v_cvt_pk_bf16_f32 v4, v18, v19
	v_cvt_pk_bf16_f32 v5, v2, v3
	v_lshl_add_u64 v[2:3], s[58:59], 0, v[16:17]
	global_store_dwordx2 v[28:29], v[36:37], off
	global_store_dwordx2 v[2:3], v[4:5], off
	s_and_saveexec_b64 s[18:19], s[0:1]
	s_cbranch_execz .LBB0_915
	s_waitcnt lgkmcnt(0)
	v_add_f32_e32 v0, v0, v1
	ds_add_f32 v159, v0
	s_branch .LBB0_915
